# P2b s5_sample: the last two per-item loads (decay, skip weight) also issued at item top
# baseline (speedup 1.0000x reference)
.LBB0_538:
	v_ashrrev_i32_e32 v8, 5, v3
	v_ashrrev_i32_e32 v9, 31, v8
	v_and_b32_e32 v22, 31, v3
	s_waitcnt lgkmcnt(0)
	v_lshlrev_b64 v[12:13], 5, v[8:9]
	v_or_b32_e32 v12, v12, v22
	v_lshlrev_b64 v[10:11], 5, v[12:13]
	v_lshl_add_u64 v[10:11], s[24:25], 0, v[10:11]
	global_load_dwordx4 v[24:27], v[10:11], off offset:16
	global_load_dwordx4 v[28:31], v[10:11], off
	v_lshl_or_b32 v96, v22, 12, v21
	global_load_dword v64, v96, s[8:9]
	global_load_dword v80, v96, s[10:11]
	global_load_dword v65, v96, s[8:9] offset:256
	global_load_dword v81, v96, s[10:11] offset:256
	global_load_dword v66, v96, s[8:9] offset:512
	global_load_dword v82, v96, s[10:11] offset:512
	global_load_dword v67, v96, s[8:9] offset:768
	global_load_dword v83, v96, s[10:11] offset:768
	global_load_dword v68, v96, s[8:9] offset:1024
	global_load_dword v84, v96, s[10:11] offset:1024
	global_load_dword v69, v96, s[8:9] offset:1280
	global_load_dword v85, v96, s[10:11] offset:1280
	global_load_dword v70, v96, s[8:9] offset:1536
	global_load_dword v86, v96, s[10:11] offset:1536
	global_load_dword v71, v96, s[8:9] offset:1792
	global_load_dword v87, v96, s[10:11] offset:1792
	global_load_dword v72, v96, s[8:9] offset:2048
	global_load_dword v88, v96, s[10:11] offset:2048
	global_load_dword v73, v96, s[8:9] offset:2304
	global_load_dword v89, v96, s[10:11] offset:2304
	global_load_dword v74, v96, s[8:9] offset:2560
	global_load_dword v90, v96, s[10:11] offset:2560
	global_load_dword v75, v96, s[8:9] offset:2816
	global_load_dword v91, v96, s[10:11] offset:2816
	global_load_dword v76, v96, s[8:9] offset:3072
	global_load_dword v92, v96, s[10:11] offset:3072
	global_load_dword v77, v96, s[8:9] offset:3328
	global_load_dword v93, v96, s[10:11] offset:3328
	global_load_dword v78, v96, s[8:9] offset:3584
	global_load_dword v94, v96, s[10:11] offset:3584
	global_load_dword v79, v96, s[8:9] offset:3840
	global_load_dword v95, v96, s[10:11] offset:3840
	v_readlane_b32 s4, v250, 39
	v_readlane_b32 s5, v250, 40
	s_nop 1
	v_lshl_or_b32 v97, v22, 6, v2
	v_lshlrev_b32_e32 v98, 3, v97
	v_lshlrev_b32_e32 v99, 7, v97
	v_lshlrev_b64 v[136:137], 8, v[12:13]
	v_lshl_or_b32 v136, v2, 2, v136
	v_lshl_add_u64 v[138:139], s[76:77], 0, v[136:137]
	v_lshl_add_u64 v[140:141], s[78:79], 0, v[136:137]
	global_load_dwordx2 v[132:133], v98, s[4:5]
	global_load_dwordx4 v[100:103], v99, s[2:3] offset:48
	global_load_dwordx4 v[104:107], v99, s[2:3] offset:32
	global_load_dwordx4 v[108:111], v99, s[2:3] offset:16
	global_load_dwordx4 v[112:115], v99, s[2:3]
	global_load_dwordx4 v[116:119], v99, s[2:3] offset:112
	global_load_dwordx4 v[120:123], v99, s[2:3] offset:96
	global_load_dwordx4 v[124:127], v99, s[2:3] offset:80
	global_load_dwordx4 v[128:131], v99, s[2:3] offset:64
	global_load_dword v134, v[138:139], off
	global_load_dword v135, v[140:141], off
	v_lshlrev_b32_e32 v144, 1, v6
	v_mov_b32_e32 v145, 0
	v_lshl_add_u64 v[146:147], v[10:11], 0, v[144:145]
	global_load_ushort v142, v[146:147], off
	v_lshlrev_b32_e32 v148, 2, v6
	v_lshl_or_b32 v148, v22, 6, v148
	global_load_dword v143, v148, s[12:13]
	s_waitcnt vmcnt(46)
	v_lshlrev_b32_e32 v48, 16, v24
	v_and_b32_e32 v49, 0xffff0000, v24
	v_lshl_or_b32 v24, v22, 6, v2
	v_lshlrev_b32_e32 v14, 3, v24
	v_lshlrev_b32_e32 v56, 7, v24
	s_waitcnt vmcnt(45)
	v_lshlrev_b32_e32 v4, 16, v28
	v_and_b32_e32 v23, 0xffff0000, v28
	v_lshlrev_b32_e32 v32, 16, v29
	v_and_b32_e32 v33, 0xffff0000, v29
	v_lshlrev_b32_e32 v44, 16, v30
	v_and_b32_e32 v45, 0xffff0000, v30
	v_lshlrev_b32_e32 v46, 16, v31
	v_and_b32_e32 v47, 0xffff0000, v31
	v_lshlrev_b32_e32 v50, 16, v25
	v_and_b32_e32 v51, 0xffff0000, v25
	v_lshlrev_b32_e32 v52, 16, v26
	v_and_b32_e32 v53, 0xffff0000, v26
	v_lshlrev_b32_e32 v54, 16, v27
	v_and_b32_e32 v55, 0xffff0000, v27
	s_mov_b32 s4, 0x42f0000
	s_waitcnt vmcnt(0)
	v_fma_f32 v57, v112, v4, 0
	v_fma_f32 v58, v113, v4, 0
	v_fmac_f32_e32 v57, v114, v23
	v_fmac_f32_e32 v58, v115, v23
	v_fmac_f32_e32 v57, v108, v32
	v_fmac_f32_e32 v58, v109, v32
	v_fmac_f32_e32 v57, v110, v33
	v_fmac_f32_e32 v58, v111, v33
	v_fmac_f32_e32 v57, v104, v44
	v_fmac_f32_e32 v58, v105, v44
	v_fmac_f32_e32 v57, v106, v45
	v_fmac_f32_e32 v58, v107, v45
	v_fmac_f32_e32 v57, v100, v46
	v_fmac_f32_e32 v58, v101, v46
	v_fmac_f32_e32 v57, v102, v47
	v_fmac_f32_e32 v58, v103, v47
	v_fmac_f32_e32 v57, v128, v48
	v_fmac_f32_e32 v58, v129, v48
	v_fmac_f32_e32 v57, v130, v49
	v_fmac_f32_e32 v58, v131, v49
	v_fmac_f32_e32 v57, v124, v50
	v_fmac_f32_e32 v58, v125, v50
	v_fmac_f32_e32 v57, v126, v51
	v_fmac_f32_e32 v58, v127, v51
	v_fmac_f32_e32 v57, v120, v52
	v_fmac_f32_e32 v58, v121, v52
	v_fmac_f32_e32 v57, v122, v53
	v_fmac_f32_e32 v58, v123, v53
	v_fmac_f32_e32 v57, v116, v54
	v_fmac_f32_e32 v58, v117, v54
	v_lshlrev_b64 v[24:25], 8, v[12:13]
	v_lshl_or_b32 v24, v2, 2, v24
	v_fmac_f32_e32 v57, v118, v55
	v_fmac_f32_e32 v58, v119, v55
	v_lshl_or_b32 v13, v22, 12, v21
	s_nop 0
	v_mul_f32_e32 v4, v133, v135
	v_mul_f32_e32 v12, v132, v135
	v_fma_f32 v4, v132, v134, -v4
	v_fmac_f32_e32 v12, v133, v134
	v_lshl_add_u64 v[14:15], s[90:91], 0, v[24:25]
	v_add_co_u32_e32 v24, vcc, s4, v14
	s_mov_b32 s4, 0x43f0000
	s_nop 0
	v_addc_co_u32_e32 v25, vcc, 0, v15, vcc
	v_add_co_u32_e32 v14, vcc, s4, v14
	v_add_f32_e32 v4, v57, v4
	v_add_f32_e32 v12, v58, v12
	v_addc_co_u32_e32 v15, vcc, 0, v15, vcc
	global_store_dword v[24:25], v4, off
	global_store_dword v[14:15], v12, off
	v_mul_f32_e32 v15, v12, v80
	v_fma_f32 v14, v4, v64, -v15
	v_mul_f32_e32 v23, v12, v81
	v_fma_f32 v15, v4, v65, -v23
	v_mul_f32_e32 v24, v12, v82
	v_fma_f32 v23, v4, v66, -v24
	v_mul_f32_e32 v25, v12, v83
	v_fma_f32 v24, v4, v67, -v25
	v_mul_f32_e32 v26, v12, v84
	v_fma_f32 v25, v4, v68, -v26
	v_mul_f32_e32 v27, v12, v85
	v_fma_f32 v26, v4, v69, -v27
	v_mul_f32_e32 v28, v12, v86
	v_fma_f32 v27, v4, v70, -v28
	v_mul_f32_e32 v29, v12, v87
	v_fma_f32 v28, v4, v71, -v29
	v_mul_f32_e32 v30, v12, v88
	v_fma_f32 v29, v4, v72, -v30
	v_mul_f32_e32 v31, v12, v89
	v_fma_f32 v30, v4, v73, -v31
	v_mul_f32_e32 v32, v12, v90
	v_fma_f32 v31, v4, v74, -v32
	v_mul_f32_e32 v33, v12, v91
	v_fma_f32 v32, v4, v75, -v33
	v_mul_f32_e32 v36, v12, v92
	v_fma_f32 v33, v4, v76, -v36
	v_mul_f32_e32 v37, v12, v93
	v_fma_f32 v36, v4, v77, -v37
	v_mul_f32_e32 v38, v12, v94
	v_fma_f32 v37, v4, v78, -v38
	v_mul_f32_e32 v12, v12, v95
	v_cndmask_b32_e64 v13, v14, v29, s[38:39]
	ds_bpermute_b32 v13, v7, v13
	v_fma_f32 v4, v4, v79, -v12
	v_cndmask_b32_e64 v12, v29, v14, s[38:39]
	v_cndmask_b32_e64 v14, v15, v30, s[38:39]
	ds_bpermute_b32 v14, v7, v14
	s_waitcnt lgkmcnt(1)
	v_add_f32_e32 v12, v12, v13
	v_cndmask_b32_e64 v13, v30, v15, s[38:39]
	v_cndmask_b32_e64 v15, v23, v31, s[38:39]
	ds_bpermute_b32 v15, v7, v15
	s_waitcnt lgkmcnt(1)
	v_add_f32_e32 v13, v13, v14
	v_cndmask_b32_e64 v14, v31, v23, s[38:39]
	v_cndmask_b32_e64 v23, v24, v32, s[38:39]
	ds_bpermute_b32 v23, v7, v23
	s_waitcnt lgkmcnt(1)
	v_add_f32_e32 v14, v14, v15
	v_cndmask_b32_e64 v15, v32, v24, s[38:39]
	v_cndmask_b32_e64 v24, v25, v33, s[38:39]
	ds_bpermute_b32 v24, v7, v24
	s_waitcnt lgkmcnt(1)
	v_add_f32_e32 v15, v15, v23
	v_cndmask_b32_e64 v23, v33, v25, s[38:39]
	v_cndmask_b32_e64 v25, v26, v36, s[38:39]
	ds_bpermute_b32 v25, v7, v25
	s_waitcnt lgkmcnt(1)
	v_add_f32_e32 v23, v23, v24
	v_cndmask_b32_e64 v24, v36, v26, s[38:39]
	v_cndmask_b32_e64 v26, v27, v37, s[38:39]
	ds_bpermute_b32 v26, v7, v26
	s_waitcnt lgkmcnt(1)
	v_add_f32_e32 v24, v24, v25
	v_cndmask_b32_e64 v25, v37, v27, s[38:39]
	s_waitcnt lgkmcnt(0)
	v_add_f32_e32 v25, v25, v26
	v_cndmask_b32_e64 v26, v4, v28, s[38:39]
	v_cndmask_b32_e64 v4, v28, v4, s[38:39]
	ds_bpermute_b32 v4, v7, v4
	s_waitcnt lgkmcnt(0)
	v_add_f32_e32 v4, v26, v4
	v_cndmask_b32_e64 v26, v23, v12, s[40:41]
	v_cndmask_b32_e64 v12, v12, v23, s[40:41]
	v_cndmask_b32_e64 v23, v24, v13, s[40:41]
	v_cndmask_b32_e64 v13, v13, v24, s[40:41]
	ds_bpermute_b32 v13, v16, v13
	ds_bpermute_b32 v12, v16, v12
	s_waitcnt lgkmcnt(1)
	v_add_f32_e32 v13, v23, v13
	v_cndmask_b32_e64 v23, v25, v14, s[40:41]
	v_cndmask_b32_e64 v14, v14, v25, s[40:41]
	ds_bpermute_b32 v14, v16, v14
	s_waitcnt lgkmcnt(1)
	v_add_f32_e32 v12, v26, v12
	s_waitcnt lgkmcnt(0)
	v_add_f32_e32 v14, v23, v14
	v_cndmask_b32_e64 v23, v4, v15, s[40:41]
	v_cndmask_b32_e64 v4, v15, v4, s[40:41]
	ds_bpermute_b32 v4, v16, v4
	v_cndmask_b32_e64 v15, v14, v12, s[42:43]
	v_cndmask_b32_e64 v12, v12, v14, s[42:43]
	ds_bpermute_b32 v12, v17, v12
	s_waitcnt lgkmcnt(1)
	v_add_f32_e32 v4, v23, v4
	v_cndmask_b32_e64 v14, v4, v13, s[42:43]
	v_cndmask_b32_e64 v4, v13, v4, s[42:43]
	ds_bpermute_b32 v4, v17, v4
	s_waitcnt lgkmcnt(1)
	v_add_f32_e32 v12, v15, v12
	s_waitcnt lgkmcnt(0)
	v_add_f32_e32 v4, v14, v4
	v_cndmask_b32_e64 v13, v4, v12, s[44:45]
	v_cndmask_b32_e64 v4, v12, v4, s[44:45]
	ds_bpermute_b32 v4, v18, v4
	s_waitcnt lgkmcnt(0)
	v_add_f32_e32 v4, v13, v4
	ds_bpermute_b32 v12, v19, v4
	s_waitcnt lgkmcnt(0)
	v_add_f32_e32 v12, v4, v12
	ds_bpermute_b32 v13, v20, v12
	s_and_saveexec_b64 s[28:29], s[46:47]
	s_cbranch_execz .LBB0_537
	v_lshlrev_b32_e32 v4, 1, v6
	v_lshl_add_u64 v[10:11], v[10:11], 0, v[4:5]
	s_nop 0
	v_lshlrev_b32_e32 v10, 2, v6
	v_lshl_or_b32 v10, v22, 6, v10
	s_nop 0
	s_waitcnt lgkmcnt(0)
	v_add_f32_e32 v12, v12, v13
	v_lshlrev_b64 v[8:9], 10, v[8:9]
	v_lshlrev_b32_e32 v10, 5, v22
	v_lshl_add_u64 v[8:9], s[68:69], 0, v[8:9]
	s_nop 0
	v_lshlrev_b32_e32 v11, 16, v142
	s_nop 0
	v_fmac_f32_e32 v12, v143, v11
	v_mul_f32_e32 v11, 0x3d372713, v12
	v_mul_f32_e32 v11, v12, v11
	v_fma_f32 v11, v12, v11, v12
	v_mul_f32_e32 v11, 0x3fcc422a, v11
	v_mul_f32_e32 v11, 0xbfb8aa3b, v11
	v_exp_f32_e32 v13, v11
	v_mov_b32_e32 v11, v5
	v_lshl_add_u64 v[8:9], v[8:9], 0, v[10:11]
	v_lshl_add_u64 v[8:9], v[8:9], 0, v[4:5]
	v_add_f32_e32 v10, 1.0, v13
	v_rcp_f32_e32 v10, v10
	v_add_co_u32_e32 v8, vcc, 0x1020000, v8
	v_mul_f32_e32 v4, v12, v10
	s_nop 0
	v_addc_co_u32_e32 v9, vcc, 0, v9, vcc
	v_cvt_pk_bf16_f32 v4, v4, v5
	global_store_short v[8:9], v4, off
	s_branch .LBB0_537
